# attention output epilogue: LDS transpose + 8 dwordx4 row stores per lane instead of 64 short stores; plus K swizzle fix
# speedup vs baseline: 1.0097x; 1.0053x over previous
; DI unsigned cvtpk(float lo, float hi) { f32x2 v = {lo, hi}; bf16x2_t b = __builtin_convertvector(v, bf16x2_t); return __builtin_bit_cast(unsigned, b); }
; DI int crow(int i, int h) { return (i & 3) + 8 * (i >> 2) + 4 * h; }
; template <typename TQ>
; __device__ __forceinline__ void attn_dense_body(const TQ* __restrict__ Qb, const bf16* __restrict__ Kh, const bf16* __restrict__ Vh,
;                                                 bf16* __restrict__ Ob, int seq, char* lds, const int tid) {
;     ...
;   if (hi == 0) li_l[r32] = l_reg; asm volatile("s_waitcnt lgkmcnt(0)" ::: "memory");
;   float rli[16];
; #pragma unroll
;   for (int r = 0; r < 16; ++r) rli[r] = __builtin_amdgcn_rcpf(li_l[crow(r, hi)]);
;   bf16* Ow = Ob + (long)(wid * QBLK) * LDO;
; #pragma unroll
;   for (int r = 0; r < 16; ++r) { int orow = crow(r, hi);
;     for (int d0 = 0; d0 < 4; ++d0) Ow[(long)orow * LDO + d0 * 32 + r32] = (bf16)(::cvtpk(o[d0][r] * rli[r], 0.f) & 0xffffu); }
.LBB0_1527:
	s_or_b64 exec, exec, s[4:5]
	s_waitcnt lgkmcnt(0)
	v_add_u32_e32 v72, s8, v176
	ds_read_b128 v[64:67], v72
	ds_read_b128 v[68:71], v72 offset:32
	s_lshl_b64 s[4:5], s[18:19], 11
	v_readlane_b32 s6, v254, 31
	v_readlane_b32 s7, v254, 32
	s_add_u32 s4, s6, s4
	s_addc_u32 s5, s7, s5
	s_lshl_b32 s6, s15, 1
	s_add_u32 s6, s4, s6
	s_waitcnt lgkmcnt(1)
	v_rcp_f32_e32 v73, v64
	v_rcp_f32_e32 v74, v65
	v_rcp_f32_e32 v75, v66
	v_rcp_f32_e32 v76, v67
	ds_read_b128 v[64:67], v72 offset:64
	s_addc_u32 s7, s5, 0
	s_ashr_i32 s21, s20, 31
	s_lshl_b64 s[4:5], s[20:21], 11
	s_add_u32 s4, s6, s4
	s_addc_u32 s5, s7, s5
	v_lshlrev_b32_e32 v176, 1, v183
	s_waitcnt lgkmcnt(1)
	v_rcp_f32_e32 v77, v68
	v_rcp_f32_e32 v78, v69
	v_rcp_f32_e32 v79, v70
	v_rcp_f32_e32 v80, v71
	ds_read_b128 v[68:71], v72 offset:96
	s_waitcnt lgkmcnt(1)
	v_rcp_f32_e32 v72, v64
	v_rcp_f32_e32 v81, v65
	v_rcp_f32_e32 v82, v66
	v_rcp_f32_e32 v83, v67
	s_waitcnt lgkmcnt(0)
	v_rcp_f32_e32 v68, v68
	v_rcp_f32_e32 v69, v69
	v_rcp_f32_e32 v70, v70
	v_rcp_f32_e32 v71, v71
	s_sub_i32 s6, s8, 0x10000
	s_mul_i32 s6, s6, 34
	s_add_i32 s6, s6, 0x10800
	v_mul_u32_u24_e32 v64, 0x440, v182
	v_lshl_add_u32 v64, v183, 1, v64
	v_add_u32_e32 v64, s6, v64
	v_mul_f32_e32 v84, v0, v73
	v_mul_f32_e32 v85, v48, v73
	v_cvt_pk_bf16_f32 v84, v84, v85
	ds_write_b16 v64, v84 offset:0
	ds_write_b16_d16_hi v64, v84 offset:64
	v_mul_f32_e32 v86, v32, v73
	v_mul_f32_e32 v87, v16, v73
	v_cvt_pk_bf16_f32 v86, v86, v87
	ds_write_b16 v64, v86 offset:128
	ds_write_b16_d16_hi v64, v86 offset:192
	v_mul_f32_e32 v88, v1, v74
	v_mul_f32_e32 v89, v49, v74
	v_cvt_pk_bf16_f32 v88, v88, v89
	ds_write_b16 v64, v88 offset:272
	ds_write_b16_d16_hi v64, v88 offset:336
	v_mul_f32_e32 v90, v33, v74
	v_mul_f32_e32 v91, v17, v74
	v_cvt_pk_bf16_f32 v90, v90, v91
	ds_write_b16 v64, v90 offset:400
	ds_write_b16_d16_hi v64, v90 offset:464
	v_mul_f32_e32 v92, v2, v75
	v_mul_f32_e32 v93, v50, v75
	v_cvt_pk_bf16_f32 v92, v92, v93
	ds_write_b16 v64, v92 offset:544
	ds_write_b16_d16_hi v64, v92 offset:608
	v_mul_f32_e32 v94, v34, v75
	v_mul_f32_e32 v95, v18, v75
	v_cvt_pk_bf16_f32 v94, v94, v95
	ds_write_b16 v64, v94 offset:672
	ds_write_b16_d16_hi v64, v94 offset:736
	v_mul_f32_e32 v84, v3, v76
	v_mul_f32_e32 v85, v51, v76
	v_cvt_pk_bf16_f32 v84, v84, v85
	ds_write_b16 v64, v84 offset:816
	ds_write_b16_d16_hi v64, v84 offset:880
	v_mul_f32_e32 v86, v35, v76
	v_mul_f32_e32 v87, v19, v76
	v_cvt_pk_bf16_f32 v86, v86, v87
	ds_write_b16 v64, v86 offset:944
	ds_write_b16_d16_hi v64, v86 offset:1008
	v_mul_f32_e32 v88, v4, v77
	v_mul_f32_e32 v89, v52, v77
	v_cvt_pk_bf16_f32 v88, v88, v89
	ds_write_b16 v64, v88 offset:2176
	ds_write_b16_d16_hi v64, v88 offset:2240
	v_mul_f32_e32 v90, v36, v77
	v_mul_f32_e32 v91, v20, v77
	v_cvt_pk_bf16_f32 v90, v90, v91
	ds_write_b16 v64, v90 offset:2304
	ds_write_b16_d16_hi v64, v90 offset:2368
	v_mul_f32_e32 v92, v5, v78
	v_mul_f32_e32 v93, v53, v78
	v_cvt_pk_bf16_f32 v92, v92, v93
	ds_write_b16 v64, v92 offset:2448
	ds_write_b16_d16_hi v64, v92 offset:2512
	v_mul_f32_e32 v94, v37, v78
	v_mul_f32_e32 v95, v21, v78
	v_cvt_pk_bf16_f32 v94, v94, v95
	ds_write_b16 v64, v94 offset:2576
	ds_write_b16_d16_hi v64, v94 offset:2640
	v_mul_f32_e32 v84, v6, v79
	v_mul_f32_e32 v85, v54, v79
	v_cvt_pk_bf16_f32 v84, v84, v85
	ds_write_b16 v64, v84 offset:2720
	ds_write_b16_d16_hi v64, v84 offset:2784
	v_mul_f32_e32 v86, v38, v79
	v_mul_f32_e32 v87, v22, v79
	v_cvt_pk_bf16_f32 v86, v86, v87
	ds_write_b16 v64, v86 offset:2848
	ds_write_b16_d16_hi v64, v86 offset:2912
	v_mul_f32_e32 v88, v7, v80
	v_mul_f32_e32 v89, v55, v80
	v_cvt_pk_bf16_f32 v88, v88, v89
	ds_write_b16 v64, v88 offset:2992
	ds_write_b16_d16_hi v64, v88 offset:3056
	v_mul_f32_e32 v90, v39, v80
	v_mul_f32_e32 v91, v23, v80
	v_cvt_pk_bf16_f32 v90, v90, v91
	ds_write_b16 v64, v90 offset:3120
	ds_write_b16_d16_hi v64, v90 offset:3184
	v_mul_f32_e32 v92, v8, v72
	v_mul_f32_e32 v93, v56, v72
	v_cvt_pk_bf16_f32 v92, v92, v93
	ds_write_b16 v64, v92 offset:4352
; DI unsigned cvtpk(float lo, float hi) { f32x2 v = {lo, hi}; bf16x2_t b = __builtin_convertvector(v, bf16x2_t); return __builtin_bit_cast(unsigned, b); }
; DI int crow(int i, int h) { return (i & 3) + 8 * (i >> 2) + 4 * h; }
; template <typename TQ>
; __device__ __forceinline__ void attn_dense_body(const TQ* __restrict__ Qb, const bf16* __restrict__ Kh, const bf16* __restrict__ Vh,
;                                                 bf16* __restrict__ Ob, int seq, char* lds, const int tid) {
;     ...
;   bf16* Ow = Ob + (long)(wid * QBLK) * LDO;
; #pragma unroll
;   for (int r = 0; r < 16; ++r) { int orow = crow(r, hi);
;     for (int d0 = 0; d0 < 4; ++d0) Ow[(long)orow * LDO + d0 * 32 + r32] = (bf16)(::cvtpk(o[d0][r] * rli[r], 0.f) & 0xffffu); }
	ds_write_b16_d16_hi v64, v92 offset:4416
	v_mul_f32_e32 v94, v40, v72
	v_mul_f32_e32 v95, v24, v72
	v_cvt_pk_bf16_f32 v94, v94, v95
	ds_write_b16 v64, v94 offset:4480
	ds_write_b16_d16_hi v64, v94 offset:4544
	v_mul_f32_e32 v84, v9, v81
	v_mul_f32_e32 v85, v57, v81
	v_cvt_pk_bf16_f32 v84, v84, v85
	ds_write_b16 v64, v84 offset:4624
	ds_write_b16_d16_hi v64, v84 offset:4688
	v_mul_f32_e32 v86, v41, v81
	v_mul_f32_e32 v87, v25, v81
	v_cvt_pk_bf16_f32 v86, v86, v87
	ds_write_b16 v64, v86 offset:4752
	ds_write_b16_d16_hi v64, v86 offset:4816
	v_mul_f32_e32 v88, v10, v82
	v_mul_f32_e32 v89, v58, v82
	v_cvt_pk_bf16_f32 v88, v88, v89
	ds_write_b16 v64, v88 offset:4896
	ds_write_b16_d16_hi v64, v88 offset:4960
	v_mul_f32_e32 v90, v42, v82
	v_mul_f32_e32 v91, v26, v82
	v_cvt_pk_bf16_f32 v90, v90, v91
	ds_write_b16 v64, v90 offset:5024
	ds_write_b16_d16_hi v64, v90 offset:5088
	v_mul_f32_e32 v92, v11, v83
	v_mul_f32_e32 v93, v59, v83
	v_cvt_pk_bf16_f32 v92, v92, v93
	ds_write_b16 v64, v92 offset:5168
	ds_write_b16_d16_hi v64, v92 offset:5232
	v_mul_f32_e32 v94, v43, v83
	v_mul_f32_e32 v95, v27, v83
	v_cvt_pk_bf16_f32 v94, v94, v95
	ds_write_b16 v64, v94 offset:5296
	ds_write_b16_d16_hi v64, v94 offset:5360
	v_mul_f32_e32 v84, v12, v68
	v_mul_f32_e32 v85, v60, v68
	v_cvt_pk_bf16_f32 v84, v84, v85
	ds_write_b16 v64, v84 offset:6528
	ds_write_b16_d16_hi v64, v84 offset:6592
	v_mul_f32_e32 v86, v44, v68
	v_mul_f32_e32 v87, v28, v68
	v_cvt_pk_bf16_f32 v86, v86, v87
	ds_write_b16 v64, v86 offset:6656
	ds_write_b16_d16_hi v64, v86 offset:6720
	v_mul_f32_e32 v88, v13, v69
	v_mul_f32_e32 v89, v61, v69
	v_cvt_pk_bf16_f32 v88, v88, v89
	ds_write_b16 v64, v88 offset:6800
	ds_write_b16_d16_hi v64, v88 offset:6864
	v_mul_f32_e32 v90, v45, v69
	v_mul_f32_e32 v91, v29, v69
	v_cvt_pk_bf16_f32 v90, v90, v91
	ds_write_b16 v64, v90 offset:6928
	ds_write_b16_d16_hi v64, v90 offset:6992
	v_mul_f32_e32 v92, v14, v70
	v_mul_f32_e32 v93, v62, v70
	v_cvt_pk_bf16_f32 v92, v92, v93
	ds_write_b16 v64, v92 offset:7072
	ds_write_b16_d16_hi v64, v92 offset:7136
	v_mul_f32_e32 v94, v46, v70
	v_mul_f32_e32 v95, v30, v70
	v_cvt_pk_bf16_f32 v94, v94, v95
	ds_write_b16 v64, v94 offset:7200
	ds_write_b16_d16_hi v64, v94 offset:7264
	v_mul_f32_e32 v84, v15, v71
	v_mul_f32_e32 v85, v63, v71
	v_cvt_pk_bf16_f32 v84, v84, v85
	ds_write_b16 v64, v84 offset:7344
	ds_write_b16_d16_hi v64, v84 offset:7408
	v_mul_f32_e32 v86, v47, v71
	v_mul_f32_e32 v87, v31, v71
	v_cvt_pk_bf16_f32 v86, v86, v87
	ds_write_b16 v64, v86 offset:7472
	ds_write_b16_d16_hi v64, v86 offset:7536
	v_lshrrev_b32_e32 v66, 4, v183
	v_lshl_add_u32 v66, v182, 1, v66
	v_mul_u32_u24_e32 v67, 0x110, v66
	v_and_b32_e32 v65, 15, v183
	v_lshl_add_u32 v67, v65, 4, v67
	v_add_u32_e32 v67, s6, v67
	v_lshlrev_b32_e32 v66, 11, v66
	v_lshl_add_u32 v72, v65, 4, v66
	v_add_u32_e32 v73, 0x2000, v72
	v_add_u32_e32 v74, 0x4000, v72
	v_add_u32_e32 v75, 0x6000, v72
	v_add_u32_e32 v76, 0x8000, v72
	v_add_u32_e32 v77, 0xa000, v72
	v_add_u32_e32 v78, 0xc000, v72
	v_add_u32_e32 v79, 0xe000, v72
	s_waitcnt lgkmcnt(0)
	ds_read_b128 v[96:99], v67 offset:0
	ds_read_b128 v[100:103], v67 offset:1088
	ds_read_b128 v[104:107], v67 offset:2176
	ds_read_b128 v[108:111], v67 offset:3264
	ds_read_b128 v[112:115], v67 offset:4352
	ds_read_b128 v[116:119], v67 offset:5440
	ds_read_b128 v[120:123], v67 offset:6528
	ds_read_b128 v[124:127], v67 offset:7616
	s_add_i32 s2, s2, s30
	s_waitcnt lgkmcnt(7)
	global_store_dwordx4 v72, v[96:99], s[4:5]
	s_waitcnt lgkmcnt(6)
	global_store_dwordx4 v73, v[100:103], s[4:5]
	s_waitcnt lgkmcnt(5)
	global_store_dwordx4 v74, v[104:107], s[4:5]
	s_waitcnt lgkmcnt(4)
	global_store_dwordx4 v75, v[108:111], s[4:5]
	s_waitcnt lgkmcnt(3)
	global_store_dwordx4 v76, v[112:115], s[4:5]
	s_waitcnt lgkmcnt(2)
	global_store_dwordx4 v77, v[116:119], s[4:5]
	s_waitcnt lgkmcnt(1)
	global_store_dwordx4 v78, v[120:123], s[4:5]
	s_waitcnt lgkmcnt(0)
	global_store_dwordx4 v79, v[124:127], s[4:5]
	s_cmpk_gt_i32 s2, 0x3ff
	s_cbranch_scc1 .LBB0_1547
